# cross-attention output projection (phase H) also walks its row panels in reverse so the rows the up GEMM reads first are the freshest in cache; on top of reversed down GEMM + staggered GEMM starts
# speedup vs baseline: 1.0067x; 1.0020x over previous
;     __device__ bool next(int i, Unit& u) const {
;         const long L = (long)i * G + c; if (L >= nwg) return false;
;         int wgid = (int)L; { const int q = nwg / NXCD, r = nwg % NXCD, xcd = wgid % NXCD, off = wgid / NXCD; wgid = (xcd < r ? xcd * (q + 1) : r * (q + 1) + (xcd - r) * q) + off; }
;         const int nig = WGM * nN, gid = wgid / nig, fm = gid * WGM, gsz = (nM - fm) < WGM ? (nM - fm) : WGM;
;         u.pm = fm + ((wgid % nig) % gsz); u.pn = (wgid % nig) / gsz; return true;
;     }
; __global__ void __launch_bounds__(NWAVES * 64, 2) mega_fwd(Args args) {
;     ...
;         pg8::Gemm g{QC, Wco_t, NTOK, DM, CWID, CWID, 0}; pg8::StaticOrder S; S.init(NTOK, DM, G, bx);
;         pg8::EpiRes<false> E{nullptr, XB, XB, ss2}; pg8::gemm_phase<pg8::EpiRes<false>, pg8::StaticOrder>(L, g, S, E);
.LBB0_973:
	v_readlane_b32 s4, v248, 0
	v_readlane_b32 s6, v248, 2
	s_cmp_lt_i32 s6, 14
	s_cselect_b64 s[0:1], -1, 0
	s_and_b64 s[2:3], s[0:1], s[2:3]
	s_andn2_b64 vcc, exec, s[2:3]
	v_readlane_b32 s5, v248, 1
	v_readlane_b32 s7, v248, 3
	s_cbranch_vccnz .LBB0_1008
	v_readlane_b32 s2, v248, 4
	v_readlane_b32 s6, v248, 8
	v_readlane_b32 s3, v248, 5
	v_mov_b32_e32 v0, v214
	v_mov_b32_e32 v13, v214
	s_cmpk_lt_i32 s6, 0x600
	s_cselect_b64 s[4:5], -1, 0
	s_cmpk_gt_i32 s6, 0x5ff
	v_readfirstlane_b32 s14, v13
	s_cbranch_scc1 .LBB0_976
	v_readlane_b32 s6, v248, 15
	v_readlane_b32 s7, v248, 16
	s_movk_i32 s8, 0xc1
	s_and_b64 s[6:7], s[6:7], exec
	s_cselect_b32 s6, s8, 0xc0
	v_readlane_b32 s7, v247, 37
	s_mul_i32 s6, s7, s6
	v_readlane_b32 s7, v248, 13
	s_add_i32 s6, s6, s7
	s_ashr_i32 s7, s6, 31
	s_lshr_b32 s7, s7, 26
	s_add_i32 s7, s6, s7
	s_ashr_i32 s8, s7, 6
	s_and_b32 s7, s7, 0xffc0
	s_sub_i32 s6, s6, s7
	s_bfe_i32 s7, s6, 0x80000
	s_bfe_u32 s7, s7, 0x3000c
	s_add_i32 s7, s6, s7
	s_bfe_i32 s9, s7, 0x80000
	s_and_b32 s7, s7, 0xf8
	s_sub_i32 s6, s6, s7
	s_lshl_b32 s8, s8, 3
	s_sext_i32_i16 s9, s9
	s_sext_i32_i8 s6, s6
	s_add_i32 s26, s8, s6
	s_ashr_i32 s24, s9, 3
	s_sub_i32 s26, 0xbf, s26

;     ...
;         const bool has_next = S.next(ui + 1, nxt);
;         const char* nA = has_next ? (const char*)g.A + (size_t)nxt.pm * tstepA : cA; const char* nB = has_next ? (const char*)g.Bt + (size_t)nxt.pn * tstepB : cB;
;     ...
; #pragma unroll
;         for (int a = 0; a < 2; ++a)
; #pragma unroll
;             for (int b = 0; b < 2; ++b)
; #pragma unroll
;                 for (int m = 0; m < 4; ++m)
; #pragma unroll
;                     for (int n = 0; n < 2; ++n) acc[a][b][m][n] = (f32x4){0.f, 0.f, 0.f, 0.f};
;         cur = nxt; cA = nA; cB = nB; ++ui;
.LBB0_984:
	s_sub_i32 s18, 0xbf, s18
	s_ashr_i32 s19, s18, 31
	s_lshl_b64 s[20:21], s[18:19], 18
	s_add_u32 s20, s35, s20
	s_addc_u32 s21, s38, s21
	s_and_b64 s[22:23], s[4:5], exec
	s_cselect_b32 s19, s21, s29
	s_cselect_b32 s25, s20, s28
	s_ashr_i32 s17, s16, 31
	s_lshl_b64 s[22:23], s[16:17], 18
	s_add_u32 s22, s33, s22
	s_addc_u32 s23, s34, s23
	s_and_b64 s[36:37], s[4:5], exec
	s_cselect_b32 s17, s23, s31
	s_cselect_b32 s48, s22, s30
	s_add_u32 s28, s28, 0x20080
	s_addc_u32 s29, s29, 0
	s_add_u32 s49, s30, 0x100
	v_mov_b32_e32 v0, 0
	s_addc_u32 s50, s31, 0
	s_mov_b32 s51, -2
	s_waitcnt lgkmcnt(0)
	v_mov_b32_e32 v1, v0
	v_mov_b32_e32 v2, v0
	v_mov_b32_e32 v3, v0
	v_mov_b32_e32 v4, v0
	v_mov_b32_e32 v5, v0
	v_mov_b32_e32 v6, v0
	v_mov_b32_e32 v7, v0
	v_mov_b32_e32 v16, v0
	v_mov_b32_e32 v17, v0
	v_mov_b32_e32 v18, v0
	v_mov_b32_e32 v19, v0
	v_mov_b32_e32 v20, v0
	v_mov_b32_e32 v21, v0
	v_mov_b32_e32 v22, v0
	v_mov_b32_e32 v23, v0
	v_mov_b32_e32 v32, v0
	v_mov_b32_e32 v33, v0
	v_mov_b32_e32 v34, v0
	v_mov_b32_e32 v35, v0
	v_mov_b32_e32 v36, v0
	v_mov_b32_e32 v37, v0
	v_mov_b32_e32 v38, v0
	v_mov_b32_e32 v39, v0
	v_mov_b32_e32 v48, v0
	v_mov_b32_e32 v49, v0
	v_mov_b32_e32 v50, v0
	v_mov_b32_e32 v51, v0
	v_mov_b32_e32 v52, v0
	v_mov_b32_e32 v53, v0
	v_mov_b32_e32 v54, v0
	v_mov_b32_e32 v55, v0
	v_mov_b32_e32 v8, v0
	v_mov_b32_e32 v9, v0
	v_mov_b32_e32 v10, v0
	v_mov_b32_e32 v11, v0
	v_mov_b32_e32 v12, v0
	v_mov_b32_e32 v13, v0
	v_mov_b32_e32 v14, v0
	v_mov_b32_e32 v15, v0
	v_mov_b32_e32 v24, v0
	v_mov_b32_e32 v25, v0
	v_mov_b32_e32 v26, v0
	v_mov_b32_e32 v27, v0
	v_mov_b32_e32 v28, v0
	v_mov_b32_e32 v29, v0
	v_mov_b32_e32 v30, v0
	v_mov_b32_e32 v31, v0
	v_mov_b32_e32 v40, v0
	v_mov_b32_e32 v41, v0
	v_mov_b32_e32 v42, v0
	v_mov_b32_e32 v43, v0
	v_mov_b32_e32 v44, v0
	v_mov_b32_e32 v45, v0
	v_mov_b32_e32 v46, v0
	v_mov_b32_e32 v47, v0
	v_mov_b32_e32 v56, v0
	v_mov_b32_e32 v57, v0
	v_mov_b32_e32 v58, v0
	v_mov_b32_e32 v59, v0
	v_mov_b32_e32 v60, v0
	v_mov_b32_e32 v61, v0
	v_mov_b32_e32 v62, v0
	v_mov_b32_e32 v63, v0
	v_mov_b32_e32 v64, v0
	v_mov_b32_e32 v65, v0
	v_mov_b32_e32 v66, v0
	v_mov_b32_e32 v67, v0
	v_mov_b32_e32 v68, v0
	v_mov_b32_e32 v69, v0
	v_mov_b32_e32 v70, v0
	v_mov_b32_e32 v71, v0
	v_mov_b32_e32 v80, v0
	v_mov_b32_e32 v81, v0
	v_mov_b32_e32 v82, v0
	v_mov_b32_e32 v83, v0
	v_mov_b32_e32 v84, v0
	v_mov_b32_e32 v85, v0
	v_mov_b32_e32 v86, v0
	v_mov_b32_e32 v87, v0
	v_mov_b32_e32 v96, v0
	v_mov_b32_e32 v97, v0
	v_mov_b32_e32 v98, v0
	v_mov_b32_e32 v99, v0
	v_mov_b32_e32 v100, v0
	v_mov_b32_e32 v101, v0
	v_mov_b32_e32 v102, v0
	v_mov_b32_e32 v103, v0
	v_mov_b32_e32 v112, v0
	v_mov_b32_e32 v113, v0
	v_mov_b32_e32 v114, v0
	v_mov_b32_e32 v115, v0
	v_mov_b32_e32 v116, v0
	v_mov_b32_e32 v117, v0
	v_mov_b32_e32 v118, v0
	v_mov_b32_e32 v119, v0
	v_mov_b32_e32 v72, v0
	v_mov_b32_e32 v73, v0
	v_mov_b32_e32 v74, v0
	v_mov_b32_e32 v75, v0
	v_mov_b32_e32 v76, v0
	v_mov_b32_e32 v77, v0
	v_mov_b32_e32 v78, v0
	v_mov_b32_e32 v79, v0
	v_mov_b32_e32 v88, v0
	v_mov_b32_e32 v89, v0
	v_mov_b32_e32 v90, v0
	v_mov_b32_e32 v91, v0
	v_mov_b32_e32 v92, v0
	v_mov_b32_e32 v93, v0
	v_mov_b32_e32 v94, v0
	v_mov_b32_e32 v95, v0
	v_mov_b32_e32 v104, v0
	v_mov_b32_e32 v105, v0
	v_mov_b32_e32 v106, v0
	v_mov_b32_e32 v107, v0
	v_mov_b32_e32 v108, v0
	v_mov_b32_e32 v109, v0
	v_mov_b32_e32 v110, v0
	v_mov_b32_e32 v111, v0
	v_mov_b32_e32 v120, v0
	v_mov_b32_e32 v121, v0
	v_mov_b32_e32 v122, v0
	v_mov_b32_e32 v123, v0
	v_mov_b32_e32 v124, v0
	v_mov_b32_e32 v125, v0
	v_mov_b32_e32 v126, v0
	v_mov_b32_e32 v127, v0
